# weight-conversion loop: the eight LDS reads of the store stage issued together with counted waits instead of three dependent read-wait round trips
# speedup vs baseline: 1.0064x; 1.0025x over previous
;   __device__ __forceinline__ unsigned char* W() const { return (unsigned char*)(GAS unsigned char*)ws; }
; __device__ __forceinline__ unsigned pk2(float lo, float hi) { const f32x2_t v = {lo, hi}; const bf16x2_t b = __builtin_convertvector(v, bf16x2_t); return __builtin_bit_cast(unsigned, b); }
; __device__ __forceinline__ void convert_weights(const Params& p, char* lds, int w0, int w1, int wstep, const int tid) {
;     ...
;       const int rr = tid >> 2, kc = (tid & 3) * 16;
;       const int Kd = (mat == 3) ? DFF : 1024;
;       bf16_t* base;
;       if (mat == 0) base = (bf16_t*)(p.W() + OFF_WIN + l * SZ_WIN);
;       else if (mat == 1) base = (bf16_t*)(p.W() + OFF_WOUT + l * SZ_WOUT);
;       else if (mat == 2) base = (bf16_t*)(p.W() + OFF_WGU + l * SZ_WGU);
;       else base = (bf16_t*)(p.W() + OFF_WDN + l * SZ_WDN);
;       bf16_t* dst = base + (size_t)(rt * 64 + rr) * Kd + kt * 64 + kc;
;       const float* s = tile + rr * 65 + kc;
;       uint4 a, b;
;       a.x = pk2(s[0], s[1]); a.y = pk2(s[2], s[3]); a.z = pk2(s[4], s[5]); a.w = pk2(s[6], s[7]);
;       b.x = pk2(s[8], s[9]); b.y = pk2(s[10], s[11]); b.z = pk2(s[12], s[13]); b.w = pk2(s[14], s[15]);
;       *(uint4*)dst = a; *(uint4*)(dst + 8) = b;
;     }
;     __syncthreads();
.LBB0_580:
	v_add_u32_e32 v4, s24, v24
	v_ashrrev_i32_e32 v5, 31, v4
	v_mul_lo_u32 v6, s34, v5
	v_mul_lo_u32 v7, s35, v4
	v_mad_u64_u32 v[4:5], s[2:3], s34, v4, 0
	v_add3_u32 v5, v5, v6, v7
	v_lshl_add_u64 v[4:5], v[4:5], 1, s[36:37]
	s_ashr_i32 s43, s42, 31
	v_lshl_add_u64 v[4:5], s[42:43], 1, v[4:5]
	v_lshl_add_u64 v[12:13], v[4:5], 0, v[2:3]
	ds_read2_b32 v[4:5], v25 offset1:1
	ds_read2_b32 v[6:7], v25 offset0:2 offset1:3
	ds_read2_b32 v[30:31], v25 offset0:4 offset1:5
	ds_read2_b32 v[8:9], v25 offset0:6 offset1:7
	ds_read2_b32 v[32:33], v25 offset0:8 offset1:9
	ds_read2_b32 v[10:11], v25 offset0:10 offset1:11
	ds_read2_b32 v[34:35], v25 offset0:12 offset1:13
	ds_read2_b32 v[14:15], v25 offset0:14 offset1:15
	s_add_i32 s23, s23, s52
	s_cmpk_gt_i32 s23, 0x1a3f
	s_waitcnt lgkmcnt(6)
	v_cvt_pk_bf16_f32 v4, v4, v5
	v_cvt_pk_bf16_f32 v5, v6, v7
	s_waitcnt lgkmcnt(4)
	v_cvt_pk_bf16_f32 v6, v30, v31
	v_cvt_pk_bf16_f32 v7, v8, v9
	s_waitcnt lgkmcnt(2)
	v_cvt_pk_bf16_f32 v8, v32, v33
	v_cvt_pk_bf16_f32 v9, v10, v11
	s_waitcnt lgkmcnt(0)
	v_cvt_pk_bf16_f32 v10, v34, v35
	v_cvt_pk_bf16_f32 v11, v14, v15
	global_store_dwordx4 v[12:13], v[4:7], off
	global_store_dwordx4 v[12:13], v[8:11], off offset:16
	s_barrier
	s_cbranch_scc1 .LBB0_623
